# s9 + p3_mid_hoist: P3 seam rescale second-half gate loads issued with the first half (into v[222:253]), first wait vmcnt 0->8
# speedup vs baseline: 1.0027x; 1.0027x over previous
.LBB0_419:
	s_andn2_b64 vcc, exec, s[42:43]
	s_cbranch_vccnz .LBB0_421
	s_cmp_eq_u32 s64, 8
	s_movk_i32 s12, 0x100
	s_cselect_b32 s12, s12, 0x200
	s_cselect_b32 s42, 0, 0x100
	s_add_i32 s44, s12, s62
	s_ashr_i32 s45, s44, 31
	s_lshl_b64 s[44:45], s[44:45], 16
	v_lshl_add_u64 v[156:157], v[208:209], 0, s[44:45]
	global_load_dwordx4 v[158:161], v[156:157], off
	s_add_i32 s42, s42, s62
	s_ashr_i32 s43, s42, 31
	s_lshl_b64 s[42:43], s[42:43], 16
	v_lshl_add_u64 v[2:3], v[208:209], 0, s[42:43]
	global_load_dwordx4 v[162:165], v[2:3], off
	global_load_dwordx4 v[152:155], v[156:157], off offset:1024
	global_load_dwordx4 v[148:151], v[2:3], off offset:1024
	global_load_dwordx4 v[140:143], v[2:3], off offset:2048
	global_load_dwordx4 v[132:135], v[2:3], off offset:3072
	global_load_dwordx4 v[144:147], v[156:157], off offset:2048
	global_load_dwordx4 v[136:139], v[156:157], off offset:3072
	s_add_u32 s44, s44, 0x1000
	s_addc_u32 s45, s45, 0
	s_add_u32 s42, s42, 0x1000
	s_addc_u32 s43, s43, 0
	v_lshl_add_u64 v[156:157], v[208:209], 0, s[44:45]
	v_lshl_add_u64 v[2:3], v[208:209], 0, s[42:43]
	global_load_dwordx4 v[222:225], v[156:157], off
	global_load_dwordx4 v[226:229], v[2:3], off
	global_load_dwordx4 v[230:233], v[2:3], off offset:1024
	global_load_dwordx4 v[234:237], v[156:157], off offset:1024
	global_load_dwordx4 v[238:241], v[2:3], off offset:2048
	global_load_dwordx4 v[242:245], v[2:3], off offset:3072
	global_load_dwordx4 v[246:249], v[156:157], off offset:2048
	global_load_dwordx4 v[250:253], v[156:157], off offset:3072
	s_waitcnt vmcnt(8)
	v_cvt_f32_ubyte3_e32 v167, v162
	v_cvt_f32_ubyte2_e32 v186, v160
	v_cvt_f32_ubyte3_e32 v187, v160
	v_rcp_iflag_f32_e32 v186, v186
	v_rcp_iflag_f32_e32 v187, v187
	v_cvt_f32_ubyte0_e32 v0, v158
	v_cvt_f32_ubyte1_e32 v177, v158
	v_cvt_f32_ubyte2_e32 v178, v158
	v_cvt_f32_ubyte3_e32 v179, v158
	v_cvt_f32_ubyte2_e32 v166, v162
	v_cvt_f32_ubyte1_e32 v169, v162
	v_cvt_f32_ubyte0_e32 v168, v162
	v_cvt_f32_ubyte0_e32 v180, v159
	v_cvt_f32_ubyte1_e32 v181, v159
	v_cvt_f32_ubyte2_e32 v182, v159
	v_cvt_f32_ubyte3_e32 v183, v159
	v_cvt_f32_ubyte3_e32 v159, v163
	v_cvt_f32_ubyte2_e32 v158, v163
	v_cvt_f32_ubyte1_e32 v171, v163
	v_cvt_f32_ubyte0_e32 v170, v163
	v_cvt_f32_ubyte3_e32 v163, v164
	v_cvt_f32_ubyte2_e32 v162, v164
	v_cvt_f32_ubyte2_e32 v190, v161
	v_cvt_f32_ubyte3_e32 v191, v161
	v_rcp_iflag_f32_e32 v176, v0
	v_rcp_iflag_f32_e32 v178, v178
	v_rcp_iflag_f32_e32 v179, v179
	v_pk_mul_f32 v[162:163], v[186:187], v[162:163]
	v_cvt_f32_ubyte0_e32 v0, v153
	v_cvt_f32_ubyte0_e32 v192, v152
	v_cvt_f32_ubyte1_e32 v193, v152
	v_cvt_f32_ubyte2_e32 v194, v152
	v_cvt_f32_ubyte3_e32 v152, v152
	v_rcp_iflag_f32_e32 v182, v182
	v_rcp_iflag_f32_e32 v183, v183
	v_rcp_iflag_f32_e32 v190, v190
	v_rcp_iflag_f32_e32 v191, v191
	v_pk_mul_f32 v[122:123], v[122:123], v[162:163]
	v_rcp_iflag_f32_e32 v162, v0
	v_cvt_f32_ubyte1_e32 v0, v153
	v_rcp_iflag_f32_e32 v194, v194
	v_rcp_iflag_f32_e32 v195, v152
	v_rcp_iflag_f32_e32 v163, v0
	v_cvt_f32_ubyte2_e32 v0, v153
	v_rcp_iflag_f32_e32 v152, v0
	v_cvt_f32_ubyte3_e32 v0, v153
	v_cvt_f32_ubyte0_e32 v184, v160
	v_cvt_f32_ubyte1_e32 v185, v160
	v_cvt_f32_ubyte0_e32 v188, v161
	v_cvt_f32_ubyte1_e32 v189, v161
	v_cvt_f32_ubyte3_e32 v161, v165
	v_cvt_f32_ubyte2_e32 v160, v165
	v_pk_mul_f32 v[166:167], v[178:179], v[166:167]
	v_rcp_iflag_f32_e32 v153, v0
	v_cvt_f32_ubyte1_e32 v173, v164
	v_cvt_f32_ubyte0_e32 v172, v164
	v_cvt_f32_ubyte1_e32 v175, v165
	v_cvt_f32_ubyte0_e32 v174, v165
	v_cvt_f32_ubyte3_e32 v165, v148
	v_cvt_f32_ubyte2_e32 v164, v148
	v_pk_mul_f32 v[158:159], v[182:183], v[158:159]
	v_pk_mul_f32 v[160:161], v[190:191], v[160:161]
	v_pk_mul_f32 v[130:131], v[130:131], v[166:167]
	v_cvt_f32_ubyte1_e32 v167, v149
	v_cvt_f32_ubyte0_e32 v166, v149
	v_pk_mul_f32 v[126:127], v[126:127], v[158:159]
	v_pk_mul_f32 v[118:119], v[118:119], v[160:161]
	v_cvt_f32_ubyte1_e32 v159, v148
	v_cvt_f32_ubyte0_e32 v158, v148
	v_pk_mul_f32 v[160:161], v[194:195], v[164:165]
	v_cvt_f32_ubyte3_e32 v165, v149
	v_cvt_f32_ubyte2_e32 v164, v149
	v_pk_mul_f32 v[148:149], v[162:163], v[166:167]
	v_cvt_f32_ubyte0_e32 v0, v154
	v_pk_mul_f32 v[108:109], v[108:109], v[148:149]
	v_rcp_iflag_f32_e32 v148, v0
	v_cvt_f32_ubyte1_e32 v0, v154
	v_rcp_iflag_f32_e32 v192, v192
	v_rcp_iflag_f32_e32 v193, v193
	v_pk_mul_f32 v[152:153], v[152:153], v[164:165]
	v_rcp_iflag_f32_e32 v149, v0
	v_cvt_f32_ubyte2_e32 v0, v154
	v_pk_mul_f32 v[110:111], v[110:111], v[152:153]
	v_rcp_iflag_f32_e32 v152, v0
	v_cvt_f32_ubyte3_e32 v0, v154
	v_rcp_iflag_f32_e32 v153, v0
	v_pk_mul_f32 v[158:159], v[192:193], v[158:159]
	v_cvt_f32_ubyte0_e32 v0, v155
	v_pk_mul_f32 v[112:113], v[112:113], v[158:159]
	v_cvt_f32_ubyte3_e32 v159, v150
	v_cvt_f32_ubyte2_e32 v158, v150
	v_pk_mul_f32 v[152:153], v[152:153], v[158:159]
	v_rcp_iflag_f32_e32 v158, v0
	v_cvt_f32_ubyte1_e32 v0, v155
	v_rcp_iflag_f32_e32 v159, v0
	v_cvt_f32_ubyte2_e32 v0, v155
	v_pk_mul_f32 v[114:115], v[114:115], v[160:161]
	v_cvt_f32_ubyte1_e32 v161, v150
	v_cvt_f32_ubyte0_e32 v160, v150
	v_rcp_iflag_f32_e32 v154, v0
	v_cvt_f32_ubyte3_e32 v0, v155
	v_pk_mul_f32 v[148:149], v[148:149], v[160:161]
	v_rcp_iflag_f32_e32 v155, v0
	v_cvt_f32_ubyte0_e32 v0, v144
	v_cvt_f32_ubyte1_e32 v163, v151
	v_cvt_f32_ubyte0_e32 v162, v151
	v_pk_mul_f32 v[104:105], v[104:105], v[148:149]
	v_rcp_iflag_f32_e32 v148, v0
	v_cvt_f32_ubyte1_e32 v0, v144
	v_cvt_f32_ubyte3_e32 v161, v151
	v_cvt_f32_ubyte2_e32 v160, v151
	v_pk_mul_f32 v[150:151], v[158:159], v[162:163]
	v_rcp_iflag_f32_e32 v149, v0
	v_cvt_f32_ubyte2_e32 v0, v144
	v_pk_mul_f32 v[100:101], v[100:101], v[150:151]
	v_rcp_iflag_f32_e32 v150, v0
	v_cvt_f32_ubyte3_e32 v0, v144
	v_rcp_iflag_f32_e32 v151, v0
	v_pk_mul_f32 v[106:107], v[106:107], v[152:153]
	v_cvt_f32_ubyte3_e32 v153, v140
	v_cvt_f32_ubyte2_e32 v152, v140
	v_cvt_f32_ubyte0_e32 v0, v145
	v_pk_mul_f32 v[150:151], v[150:151], v[152:153]
	v_rcp_iflag_f32_e32 v152, v0
	v_cvt_f32_ubyte1_e32 v0, v145
	v_rcp_iflag_f32_e32 v153, v0
	v_cvt_f32_ubyte2_e32 v0, v145
	v_rcp_iflag_f32_e32 v144, v0
	v_cvt_f32_ubyte3_e32 v0, v145
	v_pk_mul_f32 v[154:155], v[154:155], v[160:161]
	v_rcp_iflag_f32_e32 v145, v0
	v_pk_mul_f32 v[102:103], v[102:103], v[154:155]
	v_cvt_f32_ubyte1_e32 v155, v140
	v_cvt_f32_ubyte0_e32 v154, v140
	v_cvt_f32_ubyte1_e32 v159, v141
	v_cvt_f32_ubyte0_e32 v158, v141
	v_pk_mul_f32 v[148:149], v[148:149], v[154:155]
	v_cvt_f32_ubyte3_e32 v155, v141
	v_cvt_f32_ubyte2_e32 v154, v141
	v_pk_mul_f32 v[140:141], v[152:153], v[158:159]
	v_cvt_f32_ubyte0_e32 v0, v146
	v_pk_mul_f32 v[92:93], v[92:93], v[140:141]
	v_rcp_iflag_f32_e32 v140, v0
	v_cvt_f32_ubyte1_e32 v0, v146
	v_pk_mul_f32 v[144:145], v[144:145], v[154:155]
	v_rcp_iflag_f32_e32 v141, v0
	v_cvt_f32_ubyte2_e32 v0, v146
	v_pk_mul_f32 v[94:95], v[94:95], v[144:145]
	v_rcp_iflag_f32_e32 v144, v0
	v_cvt_f32_ubyte3_e32 v0, v146
	v_rcp_iflag_f32_e32 v145, v0
	v_pk_mul_f32 v[96:97], v[96:97], v[148:149]
	v_cvt_f32_ubyte3_e32 v149, v142
	v_cvt_f32_ubyte2_e32 v148, v142
	v_cvt_f32_ubyte0_e32 v0, v147
	v_pk_mul_f32 v[144:145], v[144:145], v[148:149]
	v_rcp_iflag_f32_e32 v148, v0
	v_cvt_f32_ubyte1_e32 v0, v147
	v_rcp_iflag_f32_e32 v149, v0
	v_cvt_f32_ubyte2_e32 v0, v147
	v_rcp_iflag_f32_e32 v146, v0
	v_cvt_f32_ubyte3_e32 v0, v147
	v_rcp_iflag_f32_e32 v147, v0
	v_pk_mul_f32 v[98:99], v[98:99], v[150:151]
	v_cvt_f32_ubyte1_e32 v151, v142
	v_cvt_f32_ubyte0_e32 v150, v142
	s_nop 0
	v_pk_mul_f32 v[140:141], v[140:141], v[150:151]
	v_cvt_f32_ubyte3_e32 v151, v143
	v_cvt_f32_ubyte2_e32 v150, v143
	v_cvt_f32_ubyte1_e32 v153, v143
	v_cvt_f32_ubyte0_e32 v152, v143
	s_nop 0
	v_pk_mul_f32 v[142:143], v[148:149], v[152:153]
	v_pk_mul_f32 v[146:147], v[146:147], v[150:151]
	s_nop 0
	s_nop 0
	v_cvt_f32_ubyte0_e32 v0, v136
	s_nop 0
	s_nop 0
	s_nop 0
	s_nop 0
	v_pk_mul_f32 v[88:89], v[88:89], v[140:141]
	v_rcp_iflag_f32_e32 v140, v0
	v_cvt_f32_ubyte1_e32 v0, v136
	v_rcp_iflag_f32_e32 v141, v0
	v_cvt_f32_ubyte2_e32 v0, v136
	v_pk_mul_f32 v[84:85], v[84:85], v[142:143]
	v_rcp_iflag_f32_e32 v142, v0
	v_cvt_f32_ubyte3_e32 v0, v136
	v_rcp_iflag_f32_e32 v143, v0
	v_pk_mul_f32 v[90:91], v[90:91], v[144:145]
	v_cvt_f32_ubyte3_e32 v145, v132
	v_cvt_f32_ubyte2_e32 v144, v132
	v_cvt_f32_ubyte0_e32 v0, v137
	v_pk_mul_f32 v[142:143], v[142:143], v[144:145]
	v_rcp_iflag_f32_e32 v144, v0
	v_cvt_f32_ubyte1_e32 v0, v137
	v_rcp_iflag_f32_e32 v145, v0
	v_pk_mul_f32 v[86:87], v[86:87], v[146:147]
	v_cvt_f32_ubyte1_e32 v147, v132
	v_cvt_f32_ubyte0_e32 v146, v132
	v_cvt_f32_ubyte1_e32 v157, v133
	v_cvt_f32_ubyte0_e32 v156, v133
	v_pk_mul_f32 v[140:141], v[140:141], v[146:147]
	v_cvt_f32_ubyte3_e32 v147, v133
	v_cvt_f32_ubyte2_e32 v146, v133
	v_pk_mul_f32 v[132:133], v[144:145], v[156:157]
	s_nop 0
	v_cvt_f32_ubyte2_e32 v0, v137
	v_rcp_iflag_f32_e32 v136, v0
	v_cvt_f32_ubyte3_e32 v0, v137
	v_rcp_iflag_f32_e32 v137, v0
	v_cvt_f32_ubyte0_e32 v0, v138
	v_pk_mul_f32 v[76:77], v[76:77], v[132:133]
	v_rcp_iflag_f32_e32 v132, v0
	v_cvt_f32_ubyte1_e32 v0, v138
	v_pk_mul_f32 v[136:137], v[136:137], v[146:147]
	v_rcp_iflag_f32_e32 v133, v0
	v_cvt_f32_ubyte2_e32 v0, v138
	v_pk_mul_f32 v[78:79], v[78:79], v[136:137]
	v_rcp_iflag_f32_e32 v136, v0
	v_cvt_f32_ubyte3_e32 v0, v138
	v_rcp_iflag_f32_e32 v137, v0
	v_pk_mul_f32 v[80:81], v[80:81], v[140:141]
	v_cvt_f32_ubyte3_e32 v141, v134
	v_cvt_f32_ubyte2_e32 v140, v134
	v_cvt_f32_ubyte0_e32 v0, v139
	v_pk_mul_f32 v[136:137], v[136:137], v[140:141]
	v_rcp_iflag_f32_e32 v140, v0
	v_cvt_f32_ubyte1_e32 v0, v139
	v_rcp_iflag_f32_e32 v141, v0
	v_cvt_f32_ubyte2_e32 v0, v139
	v_rcp_iflag_f32_e32 v138, v0
	v_cvt_f32_ubyte3_e32 v0, v139
	v_rcp_iflag_f32_e32 v139, v0
	v_pk_mul_f32 v[82:83], v[82:83], v[142:143]
	v_cvt_f32_ubyte1_e32 v143, v134
	v_cvt_f32_ubyte0_e32 v142, v134
	v_pk_mul_f32 v[132:133], v[132:133], v[142:143]
	v_cvt_f32_ubyte3_e32 v143, v135
	v_cvt_f32_ubyte2_e32 v142, v135
	v_cvt_f32_ubyte1_e32 v145, v135
	v_cvt_f32_ubyte0_e32 v144, v135
	v_pk_mul_f32 v[134:135], v[140:141], v[144:145]
	v_pk_mul_f32 v[138:139], v[138:139], v[142:143]
	v_pk_mul_f32 v[74:75], v[74:75], v[136:137]
	v_pk_mul_f32 v[72:73], v[72:73], v[132:133]
	v_pk_mul_f32 v[70:71], v[70:71], v[138:139]
	v_pk_mul_f32 v[68:69], v[68:69], v[134:135]
	s_nop 0
	s_nop 0
	s_nop 0
	s_nop 0
	v_rcp_iflag_f32_e32 v177, v177
	v_rcp_iflag_f32_e32 v180, v180
	v_rcp_iflag_f32_e32 v181, v181
	s_waitcnt vmcnt(0)
	v_cvt_f32_ubyte0_e32 v0, v222
	v_rcp_iflag_f32_e32 v2, v0
	v_cvt_f32_ubyte1_e32 v0, v222
	v_rcp_iflag_f32_e32 v3, v0
	v_cvt_f32_ubyte2_e32 v0, v222
	v_rcp_iflag_f32_e32 v164, v0
	v_cvt_f32_ubyte3_e32 v0, v222
	v_rcp_iflag_f32_e32 v165, v0
	v_cvt_f32_ubyte3_e32 v167, v226
	v_cvt_f32_ubyte2_e32 v166, v226
	v_cvt_f32_ubyte0_e32 v0, v223
	v_pk_mul_f32 v[164:165], v[164:165], v[166:167]
	v_rcp_iflag_f32_e32 v166, v0
	v_cvt_f32_ubyte1_e32 v0, v223
	v_rcp_iflag_f32_e32 v167, v0
	v_cvt_f32_ubyte2_e32 v0, v223
	v_rcp_iflag_f32_e32 v148, v0
	v_cvt_f32_ubyte3_e32 v0, v223
	v_pk_mul_f32 v[168:169], v[176:177], v[168:169]
	v_rcp_iflag_f32_e32 v149, v0
	v_pk_mul_f32 v[128:129], v[128:129], v[168:169]
	v_cvt_f32_ubyte1_e32 v169, v226
	v_cvt_f32_ubyte0_e32 v168, v226
	v_pk_mul_f32 v[2:3], v[2:3], v[168:169]
	v_cvt_f32_ubyte0_e32 v0, v224
	v_cvt_f32_ubyte3_e32 v169, v227
	v_cvt_f32_ubyte2_e32 v168, v227
	v_pk_mul_f32 v[64:65], v[64:65], v[2:3]
	v_rcp_iflag_f32_e32 v2, v0
	v_cvt_f32_ubyte1_e32 v0, v224
	v_pk_mul_f32 v[148:149], v[148:149], v[168:169]
	v_rcp_iflag_f32_e32 v3, v0
	v_cvt_f32_ubyte2_e32 v0, v224
	v_pk_mul_f32 v[62:63], v[62:63], v[148:149]
	v_rcp_iflag_f32_e32 v148, v0
	v_cvt_f32_ubyte3_e32 v0, v224
	v_pk_mul_f32 v[170:171], v[180:181], v[170:171]
	v_rcp_iflag_f32_e32 v149, v0
	v_pk_mul_f32 v[124:125], v[124:125], v[170:171]
	v_cvt_f32_ubyte1_e32 v171, v227
	v_cvt_f32_ubyte0_e32 v170, v227
	v_pk_mul_f32 v[152:153], v[166:167], v[170:171]
	v_cvt_f32_ubyte0_e32 v0, v225
	v_pk_mul_f32 v[60:61], v[60:61], v[152:153]
	v_cvt_f32_ubyte3_e32 v153, v228
	v_cvt_f32_ubyte2_e32 v152, v228
	v_pk_mul_f32 v[148:149], v[148:149], v[152:153]
	v_rcp_iflag_f32_e32 v152, v0
	v_cvt_f32_ubyte1_e32 v0, v225
	v_rcp_iflag_f32_e32 v153, v0
	v_cvt_f32_ubyte2_e32 v0, v225
	v_pk_mul_f32 v[66:67], v[66:67], v[164:165]
	v_cvt_f32_ubyte1_e32 v165, v228
	v_cvt_f32_ubyte0_e32 v164, v228
	v_rcp_iflag_f32_e32 v150, v0
	v_cvt_f32_ubyte3_e32 v0, v225
	v_pk_mul_f32 v[2:3], v[2:3], v[164:165]
	v_rcp_iflag_f32_e32 v151, v0
	v_cvt_f32_ubyte0_e32 v0, v234
	v_pk_mul_f32 v[56:57], v[56:57], v[2:3]
	v_rcp_iflag_f32_e32 v2, v0
	v_cvt_f32_ubyte1_e32 v0, v234
	v_rcp_iflag_f32_e32 v3, v0
	v_cvt_f32_ubyte2_e32 v0, v234
	v_pk_mul_f32 v[58:59], v[58:59], v[148:149]
	v_rcp_iflag_f32_e32 v148, v0
	v_cvt_f32_ubyte3_e32 v0, v234
	v_rcp_iflag_f32_e32 v149, v0
	v_cvt_f32_ubyte3_e32 v165, v229
	v_cvt_f32_ubyte2_e32 v164, v229
	v_pk_mul_f32 v[150:151], v[150:151], v[164:165]
	v_cvt_f32_ubyte1_e32 v167, v229
	v_cvt_f32_ubyte0_e32 v166, v229
	v_pk_mul_f32 v[54:55], v[54:55], v[150:151]
	v_cvt_f32_ubyte3_e32 v151, v230
	v_cvt_f32_ubyte2_e32 v150, v230
	v_cvt_f32_ubyte0_e32 v0, v235
	v_pk_mul_f32 v[152:153], v[152:153], v[166:167]
	v_pk_mul_f32 v[148:149], v[148:149], v[150:151]
	v_rcp_iflag_f32_e32 v150, v0
	v_cvt_f32_ubyte1_e32 v0, v235
	v_pk_mul_f32 v[52:53], v[52:53], v[152:153]
	v_cvt_f32_ubyte1_e32 v153, v230
	v_cvt_f32_ubyte0_e32 v152, v230
	v_rcp_iflag_f32_e32 v151, v0
	v_cvt_f32_ubyte2_e32 v0, v235
	v_pk_mul_f32 v[2:3], v[2:3], v[152:153]
	v_rcp_iflag_f32_e32 v152, v0
	v_cvt_f32_ubyte3_e32 v0, v235
	v_rcp_iflag_f32_e32 v153, v0
	v_cvt_f32_ubyte0_e32 v0, v236
	v_pk_mul_f32 v[48:49], v[48:49], v[2:3]
	v_rcp_iflag_f32_e32 v2, v0
	v_cvt_f32_ubyte1_e32 v0, v236
	v_rcp_iflag_f32_e32 v3, v0
	v_cvt_f32_ubyte2_e32 v0, v236
	v_pk_mul_f32 v[50:51], v[50:51], v[148:149]
	v_rcp_iflag_f32_e32 v148, v0
	v_cvt_f32_ubyte3_e32 v0, v236
	v_rcp_iflag_f32_e32 v149, v0
	v_cvt_f32_ubyte1_e32 v157, v231
	v_cvt_f32_ubyte0_e32 v156, v231
	v_pk_mul_f32 v[150:151], v[150:151], v[156:157]
	v_cvt_f32_ubyte3_e32 v155, v231
	v_cvt_f32_ubyte2_e32 v154, v231
	v_pk_mul_f32 v[44:45], v[44:45], v[150:151]
	v_cvt_f32_ubyte3_e32 v151, v232
	v_cvt_f32_ubyte2_e32 v150, v232
	v_cvt_f32_ubyte0_e32 v0, v237
	v_pk_mul_f32 v[152:153], v[152:153], v[154:155]
	v_pk_mul_f32 v[148:149], v[148:149], v[150:151]
	v_rcp_iflag_f32_e32 v150, v0
	v_cvt_f32_ubyte1_e32 v0, v237
	v_pk_mul_f32 v[46:47], v[46:47], v[152:153]
	v_cvt_f32_ubyte1_e32 v153, v232
	v_cvt_f32_ubyte0_e32 v152, v232
	v_rcp_iflag_f32_e32 v151, v0
	v_cvt_f32_ubyte2_e32 v0, v237
	v_pk_mul_f32 v[2:3], v[2:3], v[152:153]
	v_rcp_iflag_f32_e32 v152, v0
	v_cvt_f32_ubyte3_e32 v0, v237
	v_rcp_iflag_f32_e32 v153, v0
	v_cvt_f32_ubyte0_e32 v0, v246
	v_pk_mul_f32 v[40:41], v[40:41], v[2:3]
	v_rcp_iflag_f32_e32 v2, v0
	v_cvt_f32_ubyte1_e32 v0, v246
	v_rcp_iflag_f32_e32 v3, v0
	v_cvt_f32_ubyte2_e32 v0, v246
	v_pk_mul_f32 v[42:43], v[42:43], v[148:149]
	v_rcp_iflag_f32_e32 v148, v0
	v_cvt_f32_ubyte3_e32 v0, v246
	v_rcp_iflag_f32_e32 v149, v0
	v_cvt_f32_ubyte1_e32 v157, v233
	v_cvt_f32_ubyte0_e32 v156, v233
	v_pk_mul_f32 v[150:151], v[150:151], v[156:157]
	v_cvt_f32_ubyte0_e32 v0, v247
	v_pk_mul_f32 v[36:37], v[36:37], v[150:151]
	v_cvt_f32_ubyte3_e32 v151, v238
	v_cvt_f32_ubyte2_e32 v150, v238
	v_cvt_f32_ubyte3_e32 v155, v233
	v_cvt_f32_ubyte2_e32 v154, v233
	v_pk_mul_f32 v[148:149], v[148:149], v[150:151]
	v_rcp_iflag_f32_e32 v150, v0
	v_cvt_f32_ubyte1_e32 v0, v247
	v_pk_mul_f32 v[152:153], v[152:153], v[154:155]
	v_rcp_iflag_f32_e32 v151, v0
	v_cvt_f32_ubyte2_e32 v0, v247
	v_pk_mul_f32 v[38:39], v[38:39], v[152:153]
	v_cvt_f32_ubyte1_e32 v153, v238
	v_cvt_f32_ubyte0_e32 v152, v238
	v_rcp_iflag_f32_e32 v144, v0
	v_cvt_f32_ubyte3_e32 v0, v247
	v_pk_mul_f32 v[2:3], v[2:3], v[152:153]
	v_rcp_iflag_f32_e32 v145, v0
	v_cvt_f32_ubyte0_e32 v0, v248
	v_cvt_f32_ubyte1_e32 v155, v239
	v_cvt_f32_ubyte0_e32 v154, v239
	v_pk_mul_f32 v[32:33], v[32:33], v[2:3]
	v_rcp_iflag_f32_e32 v2, v0
	v_cvt_f32_ubyte1_e32 v0, v248
	v_cvt_f32_ubyte3_e32 v153, v239
	v_cvt_f32_ubyte2_e32 v152, v239
	v_pk_mul_f32 v[140:141], v[150:151], v[154:155]
	v_rcp_iflag_f32_e32 v3, v0
	v_cvt_f32_ubyte2_e32 v0, v248
	v_pk_mul_f32 v[28:29], v[28:29], v[140:141]
	v_rcp_iflag_f32_e32 v140, v0
	v_cvt_f32_ubyte3_e32 v0, v248
	v_rcp_iflag_f32_e32 v141, v0
	v_pk_mul_f32 v[144:145], v[144:145], v[152:153]
	v_cvt_f32_ubyte0_e32 v0, v249
	v_pk_mul_f32 v[30:31], v[30:31], v[144:145]
	v_cvt_f32_ubyte3_e32 v145, v240
	v_cvt_f32_ubyte2_e32 v144, v240
	v_pk_mul_f32 v[140:141], v[140:141], v[144:145]
	v_rcp_iflag_f32_e32 v144, v0
	v_cvt_f32_ubyte1_e32 v0, v249
	v_rcp_iflag_f32_e32 v145, v0
	v_cvt_f32_ubyte2_e32 v0, v249
	v_pk_mul_f32 v[34:35], v[34:35], v[148:149]
	v_cvt_f32_ubyte1_e32 v149, v240
	v_cvt_f32_ubyte0_e32 v148, v240
	v_rcp_iflag_f32_e32 v146, v0
	v_cvt_f32_ubyte3_e32 v0, v249
	v_pk_mul_f32 v[2:3], v[2:3], v[148:149]
	v_rcp_iflag_f32_e32 v147, v0
	v_cvt_f32_ubyte0_e32 v0, v250
	v_pk_mul_f32 v[24:25], v[24:25], v[2:3]
	v_rcp_iflag_f32_e32 v2, v0
	v_cvt_f32_ubyte1_e32 v0, v250
	v_rcp_iflag_f32_e32 v3, v0
	v_cvt_f32_ubyte2_e32 v0, v250
	v_pk_mul_f32 v[26:27], v[26:27], v[140:141]
	v_rcp_iflag_f32_e32 v140, v0
	v_cvt_f32_ubyte3_e32 v0, v250
	v_rcp_iflag_f32_e32 v141, v0
	v_cvt_f32_ubyte1_e32 v151, v241
	v_cvt_f32_ubyte0_e32 v150, v241
	v_cvt_f32_ubyte3_e32 v149, v241
	v_cvt_f32_ubyte2_e32 v148, v241
	v_pk_mul_f32 v[142:143], v[144:145], v[150:151]
	v_cvt_f32_ubyte0_e32 v0, v251
	v_pk_mul_f32 v[20:21], v[20:21], v[142:143]
	v_cvt_f32_ubyte3_e32 v143, v242
	v_cvt_f32_ubyte2_e32 v142, v242
	v_pk_mul_f32 v[140:141], v[140:141], v[142:143]
	v_rcp_iflag_f32_e32 v142, v0
	v_cvt_f32_ubyte1_e32 v0, v251
	v_pk_mul_f32 v[144:145], v[146:147], v[148:149]
	v_rcp_iflag_f32_e32 v143, v0
	v_cvt_f32_ubyte2_e32 v0, v251
	v_pk_mul_f32 v[22:23], v[22:23], v[144:145]
	v_cvt_f32_ubyte1_e32 v145, v242
	v_cvt_f32_ubyte0_e32 v144, v242
	v_rcp_iflag_f32_e32 v136, v0
	v_cvt_f32_ubyte3_e32 v0, v251
	v_pk_mul_f32 v[2:3], v[2:3], v[144:145]
	v_rcp_iflag_f32_e32 v137, v0
	v_cvt_f32_ubyte0_e32 v0, v252
	v_cvt_f32_ubyte1_e32 v147, v243
	v_cvt_f32_ubyte0_e32 v146, v243
	v_pk_mul_f32 v[16:17], v[16:17], v[2:3]
	v_rcp_iflag_f32_e32 v2, v0
	v_cvt_f32_ubyte1_e32 v0, v252
	v_cvt_f32_ubyte3_e32 v145, v243
	v_cvt_f32_ubyte2_e32 v144, v243
	v_pk_mul_f32 v[132:133], v[142:143], v[146:147]
	v_rcp_iflag_f32_e32 v3, v0
	v_cvt_f32_ubyte2_e32 v0, v252
	v_pk_mul_f32 v[12:13], v[12:13], v[132:133]
	v_rcp_iflag_f32_e32 v132, v0
	v_cvt_f32_ubyte3_e32 v0, v252
	v_rcp_iflag_f32_e32 v133, v0
	v_pk_mul_f32 v[136:137], v[136:137], v[144:145]
	v_cvt_f32_ubyte0_e32 v0, v253
	v_pk_mul_f32 v[14:15], v[14:15], v[136:137]
	v_cvt_f32_ubyte3_e32 v137, v244
	v_cvt_f32_ubyte2_e32 v136, v244
	v_pk_mul_f32 v[132:133], v[132:133], v[136:137]
	v_rcp_iflag_f32_e32 v136, v0
	v_cvt_f32_ubyte1_e32 v0, v253
	v_rcp_iflag_f32_e32 v137, v0
	v_cvt_f32_ubyte2_e32 v0, v253
	v_rcp_iflag_f32_e32 v138, v0
	v_cvt_f32_ubyte3_e32 v0, v253
	v_rcp_iflag_f32_e32 v184, v184
	v_rcp_iflag_f32_e32 v185, v185
	v_rcp_iflag_f32_e32 v188, v188
	v_rcp_iflag_f32_e32 v189, v189
	v_rcp_iflag_f32_e32 v139, v0
	v_pk_mul_f32 v[18:19], v[18:19], v[140:141]
	v_cvt_f32_ubyte1_e32 v141, v244
	v_cvt_f32_ubyte0_e32 v140, v244
	v_pk_mul_f32 v[2:3], v[2:3], v[140:141]
	v_cvt_f32_ubyte3_e32 v141, v245
	v_cvt_f32_ubyte2_e32 v140, v245
	v_cvt_f32_ubyte1_e32 v143, v245
	v_cvt_f32_ubyte0_e32 v142, v245
	v_pk_mul_f32 v[172:173], v[184:185], v[172:173]
	v_pk_mul_f32 v[174:175], v[188:189], v[174:175]
	v_pk_mul_f32 v[134:135], v[136:137], v[142:143]
	v_pk_mul_f32 v[136:137], v[138:139], v[140:141]
	v_pk_mul_f32 v[120:121], v[120:121], v[172:173]
	v_pk_mul_f32 v[116:117], v[116:117], v[174:175]
	v_pk_mul_f32 v[10:11], v[10:11], v[132:133]
	v_pk_mul_f32 v[8:9], v[8:9], v[2:3]
	v_pk_mul_f32 v[6:7], v[6:7], v[136:137]
	v_pk_mul_f32 v[4:5], v[4:5], v[134:135]
